# v83 with the L1 invalidate issued first in the flag-barrier path (before the pointer load and flag store)
# speedup vs baseline: 1.0028x; 1.0028x over previous
.LBB0_233:
	s_mov_b64 s[6:7], s[0:1]
	s_getreg_b32 s8, hwreg(HW_REG_XCC_ID, 0, 4)
	s_waitcnt vmcnt(0)
	s_waitcnt vmcnt(0)
	v_add_u32_e32 v254, v254, v255
	v_cmp_ne_u32_e32 vcc, 17, v254
	s_nop 3
	s_cmp_eq_u64 vcc, 0
	s_cselect_b32 s99, 1, 0
	s_cmpk_lg_i32 s52, 0x100
	s_cselect_b32 s99, 0, s99
	s_barrier
	s_and_saveexec_b64 s[4:5], s[44:45]
	s_xor_b64 s[4:5], exec, s[4:5]
	s_cbranch_execz .LBB0_286
	s_cmp_eq_u32 s99, 0
	s_cbranch_scc1 .Lfb_skip_0
	buffer_inv sc1
	s_load_dwordx2 s[8:9], s[0:1], 0x80
	s_and_b32 s10, s2, 7
	s_lshl_b32 s10, s10, 8
	s_add_i32 s10, s10, 0x1000
	s_lshr_b32 s11, s2, 3
	s_lshl_b32 s11, s11, 2
	v_mov_b32_e32 v1, s11
	v_mov_b32_e32 v0, 1
	s_mov_b32 s13, 0
	s_mov_b64 s[16:17], exec
	s_waitcnt lgkmcnt(0)
	s_add_u32 s8, s8, s10
	s_addc_u32 s9, s9, 0
	global_store_dword v1, v0, s[8:9]
	s_mov_b64 exec, 0xffffffff
	v_mbcnt_lo_u32_b32 v4, -1, 0
	v_lshlrev_b32_e32 v4, 2, v4
	v_mov_b32_e32 v0, 1

.LBB0_518:
	s_mov_b64 s[6:7], s[0:1]
	s_getreg_b32 s8, hwreg(HW_REG_XCC_ID, 0, 4)
	s_waitcnt vmcnt(0)
	s_barrier
	s_and_saveexec_b64 s[4:5], s[44:45]
	s_cbranch_execz .LBB0_570
	s_cmp_eq_u32 s99, 0
	s_cbranch_scc1 .Lfb_skip_1
	buffer_inv sc1
	s_load_dwordx2 s[8:9], s[0:1], 0x80
	s_and_b32 s10, s2, 7
	s_lshl_b32 s10, s10, 8
	s_add_i32 s10, s10, 0x1000
	s_lshr_b32 s11, s2, 3
	s_lshl_b32 s11, s11, 2
	v_mov_b32_e32 v1, s11
	v_mov_b32_e32 v0, 2
	s_mov_b32 s13, 0
	s_mov_b64 s[16:17], exec
	s_waitcnt lgkmcnt(0)
	s_add_u32 s8, s8, s10
	s_addc_u32 s9, s9, 0
	global_store_dword v1, v0, s[8:9]
	s_mov_b64 exec, 0xffffffff
	v_mbcnt_lo_u32_b32 v4, -1, 0
	v_lshlrev_b32_e32 v4, 2, v4
	v_mov_b32_e32 v0, 2

.LBB0_612:
	s_mov_b64 s[8:9], s[0:1]
	s_waitcnt lgkmcnt(0)
	s_getreg_b32 s10, hwreg(HW_REG_XCC_ID, 0, 4)
	s_waitcnt vmcnt(0)
	s_barrier
	s_and_saveexec_b64 s[6:7], s[44:45]
	s_cbranch_execz .LBB0_664
	s_cmp_eq_u32 s99, 0
	s_cbranch_scc1 .Lfb_skip_2
	buffer_inv sc1
	s_load_dwordx2 s[8:9], s[0:1], 0x80
	s_and_b32 s10, s2, 7
	s_lshl_b32 s10, s10, 8
	s_add_i32 s10, s10, 0x1000
	s_lshr_b32 s11, s2, 3
	s_lshl_b32 s11, s11, 2
	v_mov_b32_e32 v1, s11
	v_mov_b32_e32 v0, 3
	s_mov_b32 s13, 0
	s_mov_b64 s[16:17], exec
	s_waitcnt lgkmcnt(0)
	s_add_u32 s8, s8, s10
	s_addc_u32 s9, s9, 0
	global_store_dword v1, v0, s[8:9]
	s_mov_b64 exec, 0xffffffff
	v_mbcnt_lo_u32_b32 v4, -1, 0
	v_lshlrev_b32_e32 v4, 2, v4
	v_mov_b32_e32 v0, 3

.LBB0_1112:
	s_mov_b64 s[8:9], s[0:1]
	s_getreg_b32 s10, hwreg(HW_REG_XCC_ID, 0, 4)
	s_waitcnt vmcnt(0)
	s_barrier
	s_and_saveexec_b64 s[6:7], s[44:45]
	s_cbranch_execz .LBB0_1164
	s_cmp_eq_u32 s99, 0
	s_cbranch_scc1 .Lfb_skip_3
	buffer_inv sc1
	s_load_dwordx2 s[8:9], s[0:1], 0x80
	s_and_b32 s10, s2, 7
	s_lshl_b32 s10, s10, 8
	s_add_i32 s10, s10, 0x1000
	s_lshr_b32 s11, s2, 3
	s_lshl_b32 s11, s11, 2
	v_mov_b32_e32 v1, s11
	v_mov_b32_e32 v0, 4
	s_mov_b32 s13, 0
	s_mov_b64 s[16:17], exec
	s_waitcnt lgkmcnt(0)
	s_add_u32 s8, s8, s10
	s_addc_u32 s9, s9, 0
	global_store_dword v1, v0, s[8:9]
	s_mov_b64 exec, 0xffffffff
	v_mbcnt_lo_u32_b32 v4, -1, 0
	v_lshlrev_b32_e32 v4, 2, v4
	v_mov_b32_e32 v0, 4

.LBB0_1210:
	s_mov_b64 s[8:9], s[0:1]
	s_getreg_b32 s10, hwreg(HW_REG_XCC_ID, 0, 4)
	s_waitcnt vmcnt(0)
	s_waitcnt lgkmcnt(0)
	s_barrier
	s_and_saveexec_b64 s[6:7], s[44:45]
	s_cbranch_execz .LBB0_1262
	s_cmp_eq_u32 s99, 0
	s_cbranch_scc1 .Lfb_skip_4
	buffer_inv sc1
	s_load_dwordx2 s[8:9], s[0:1], 0x80
	s_and_b32 s10, s2, 7
	s_lshl_b32 s10, s10, 8
	s_add_i32 s10, s10, 0x1000
	s_lshr_b32 s11, s2, 3
	s_lshl_b32 s11, s11, 2
	v_mov_b32_e32 v1, s11
	v_mov_b32_e32 v0, 5
	s_mov_b32 s13, 0
	s_mov_b64 s[16:17], exec
	s_waitcnt lgkmcnt(0)
	s_add_u32 s8, s8, s10
	s_addc_u32 s9, s9, 0
	global_store_dword v1, v0, s[8:9]
	s_mov_b64 exec, 0xffffffff
	v_mbcnt_lo_u32_b32 v4, -1, 0
	v_lshlrev_b32_e32 v4, 2, v4
	v_mov_b32_e32 v0, 5

.LBB0_1349:
	s_mov_b64 s[8:9], s[0:1]
	s_getreg_b32 s10, hwreg(HW_REG_XCC_ID, 0, 4)
	s_waitcnt vmcnt(0)
	s_barrier
	s_and_saveexec_b64 s[6:7], s[44:45]
	s_cbranch_execz .LBB0_1401
	s_cmp_eq_u32 s99, 0
	s_cbranch_scc1 .Lfb_skip_5
	buffer_inv sc1
	s_load_dwordx2 s[8:9], s[0:1], 0x80
	s_and_b32 s10, s2, 7
	s_lshl_b32 s10, s10, 8
	s_add_i32 s10, s10, 0x1000
	s_lshr_b32 s11, s2, 3
	s_lshl_b32 s11, s11, 2
	v_mov_b32_e32 v1, s11
	v_mov_b32_e32 v0, 6
	s_mov_b32 s13, 0
	s_mov_b64 s[16:17], exec
	s_waitcnt lgkmcnt(0)
	s_add_u32 s8, s8, s10
	s_addc_u32 s9, s9, 0
	global_store_dword v1, v0, s[8:9]
	s_mov_b64 exec, 0xffffffff
	v_mbcnt_lo_u32_b32 v4, -1, 0
	v_lshlrev_b32_e32 v4, 2, v4
	v_mov_b32_e32 v0, 6

.LBB0_1443:
	s_mov_b64 s[8:9], s[0:1]
	s_getreg_b32 s10, hwreg(HW_REG_XCC_ID, 0, 4)
	s_waitcnt vmcnt(0)
	s_waitcnt lgkmcnt(0)
	s_barrier
	s_and_saveexec_b64 s[6:7], s[44:45]
	s_cbranch_execz .LBB0_1495
	s_cmp_eq_u32 s99, 0
	s_cbranch_scc1 .Lfb_skip_6
	buffer_inv sc1
	s_load_dwordx2 s[8:9], s[0:1], 0x80
	s_and_b32 s10, s2, 7
	s_lshl_b32 s10, s10, 8
	s_add_i32 s10, s10, 0x1000
	s_lshr_b32 s11, s2, 3
	s_lshl_b32 s11, s11, 2
	v_mov_b32_e32 v1, s11
	v_mov_b32_e32 v0, 7
	s_mov_b32 s13, 0
	s_mov_b64 s[16:17], exec
	s_waitcnt lgkmcnt(0)
	s_add_u32 s8, s8, s10
	s_addc_u32 s9, s9, 0
	global_store_dword v1, v0, s[8:9]
	s_mov_b64 exec, 0xffffffff
	v_mbcnt_lo_u32_b32 v4, -1, 0
	v_lshlrev_b32_e32 v4, 2, v4
	v_mov_b32_e32 v0, 7
